# v35 with scan dots as single packed accumulator chain (4 fewer VALU per step)
# baseline (speedup 1.0000x reference)
; __device__ __forceinline__ float dot16(const f32x4 (&S)[4], const f32x4 (&a)[4]) {
;     f32x2 p0 = (f32x2){S[0][0], S[0][1]} * (f32x2){a[0][0], a[0][1]}, p1 = (f32x2){S[0][2], S[0][3]} * (f32x2){a[0][2], a[0][3]};
; #pragma unroll
;     for (int q = 1; q < 4; ++q) { p0 = __builtin_elementwise_fma((f32x2){S[q][0], S[q][1]}, (f32x2){a[q][0], a[q][1]}, p0); p1 = __builtin_elementwise_fma((f32x2){S[q][2], S[q][3]}, (f32x2){a[q][2], a[q][3]}, p1); }
; template <bool useB>
; __device__ __forceinline__ void rw_block4(ScanState& st, const LAS unsigned char* pb, const LAS float* pv, float* outA, float* outB, int kg) {
;     f32x4 oa[4], ob[4], ok[4], orr[2][4]; float ov;
;     ...
;     RW_LD4(oa, pb); RW_LD4(ob, pb + 256); RW_LD4(ok, pb + 512); RW_LD4(orr[0], pb + 768); ov = *pv;
;     float ykA = 0.f, ykB = 0.f;
;     const f32x4 z = (f32x4){0.f, 0.f, 0.f, 0.f};
; #pragma unroll
;     for (int ss = 0; ss < 4; ++ss) {
;         const bool more = ss < 3;
;         const LAS unsigned char* pn = pb + (ss + 1) * 1024; const LAS float* vn = pv + (ss + 1) * 16;
;         const float pa = dot16(st.A, oa), pq = useB ? dot16(st.B, oa) : 0.f;
;         const f32x4 da = __builtin_amdgcn_mfma_f32_16x16x4f32(1.0f, pa, z, 0, 0, 0);
;         f32x4 db = z; if (useB) db = __builtin_amdgcn_mfma_f32_16x16x4f32(1.0f, pq, z, 0, 0, 0);
;         if (more) RW_LD4(oa, pn);
;         if (ss > 0) { const float y = ksum(dot16(st.A, orr[(ss + 1) & 1])); ykA = (kg == ss - 1) ? y : ykA;
;             if (useB) { const float c = ksum(dot16(st.B, orr[(ss + 1) & 1])); ykB = (kg == ss - 1) ? c : ykB; } }
;         if (more) RW_LD4(orr[(ss + 1) & 1], pn + 768);
;         const float sa = da[0], sb = db[0];
;         const f32x4 sa4 = (f32x4){sa, sa, sa, sa}, sb4 = (f32x4){sb, sb, sb, sb}, v4 = (f32x4){ov, ov, ov, ov};
; #pragma unroll
;         for (int e = 0; e < 4; ++e) { st.A[e] = __builtin_elementwise_fma(ob[e], sa4, st.A[e]); st.A[e] = __builtin_elementwise_fma(ok[e], v4, st.A[e]); if (useB) st.B[e] = __builtin_elementwise_fma(ob[e], sb4, st.B[e]); }
;         if (more) { RW_LD4(ob, pn + 256); RW_LD4(ok, pn + 512); ov = *vn; }
;     }
;     { const float y = ksum(dot16(st.A, orr[1])); ykA = (kg == 3) ? y : ykA; outA[(size_t)kg * DH] = ykA;
;       if (useB) { const float c = ksum(dot16(st.B, orr[1])); ykB = (kg == 3) ? c : ykB; outB[(size_t)kg * DH] = ykB; } }
.LBB0_1031:
	s_and_b32 s0, s51, 3
	v_lshl_add_u32 v85, s0, 12, v59
	v_lshl_add_u32 v111, s0, 8, v107
	ds_read_b128 v[128:131], v85
	ds_read_b128 v[132:135], v85 offset:16
	ds_read_b128 v[136:139], v85 offset:32
	ds_read_b128 v[140:143], v85 offset:48
	ds_read_b128 v[192:195], v85 offset:256
	ds_read_b128 v[196:199], v85 offset:272
	ds_read_b128 v[204:207], v85 offset:288
	ds_read_b128 v[208:211], v85 offset:304
	ds_read_b128 v[212:215], v85 offset:512
	ds_read_b128 v[216:219], v85 offset:528
	ds_read_b128 v[220:223], v85 offset:544
	ds_read_b128 v[224:227], v85 offset:560
	ds_read_b32 v16, v111
	s_waitcnt lgkmcnt(9)
	v_pk_mul_f32 v[248:249], v[36:37], v[128:129]
	v_pk_mul_f32 v[252:253], v[20:21], v[128:129]
	v_pk_fma_f32 v[248:249], v[38:39], v[130:131], v[248:249]
	v_pk_fma_f32 v[252:253], v[22:23], v[130:131], v[252:253]
	v_pk_fma_f32 v[248:249], v[40:41], v[132:133], v[248:249]
	v_pk_fma_f32 v[252:253], v[24:25], v[132:133], v[252:253]
	v_pk_fma_f32 v[248:249], v[42:43], v[134:135], v[248:249]
	v_pk_fma_f32 v[252:253], v[26:27], v[134:135], v[252:253]
	v_pk_fma_f32 v[248:249], v[48:49], v[136:137], v[248:249]
	v_pk_fma_f32 v[252:253], v[28:29], v[136:137], v[252:253]
	v_pk_fma_f32 v[248:249], v[50:51], v[138:139], v[248:249]
	v_pk_fma_f32 v[252:253], v[30:31], v[138:139], v[252:253]
	v_pk_fma_f32 v[248:249], v[44:45], v[140:141], v[248:249]
	v_pk_fma_f32 v[252:253], v[32:33], v[140:141], v[252:253]
	v_pk_fma_f32 v[248:249], v[46:47], v[142:143], v[248:249]
	v_pk_fma_f32 v[252:253], v[34:35], v[142:143], v[252:253]
	ds_read_b128 v[144:147], v85 offset:768
	ds_read_b128 v[148:151], v85 offset:784
	ds_read_b128 v[154:157], v85 offset:800
	ds_read_b128 v[158:161], v85 offset:816
	ds_read_b128 v[112:115], v85 offset:1024
	ds_read_b128 v[116:119], v85 offset:1040
	ds_read_b128 v[120:123], v85 offset:1056
	ds_read_b128 v[124:127], v85 offset:1072
	v_add_f32_e32 v2, v248, v249
	v_add_f32_e32 v18, v252, v253
	s_nop 0
	v_mfma_f32_16x16x4_f32 v[228:231], v61, v2, 0
	v_mfma_f32_16x16x4_f32 v[232:235], v61, v18, 0
	s_waitcnt lgkmcnt(0)
	s_nop 7
	v_pk_fma_f32 v[36:37], v[192:193], v[228:229], v[36:37] op_sel_hi:[1,0,1]
	v_pk_fma_f32 v[38:39], v[194:195], v[228:229], v[38:39] op_sel_hi:[1,0,1]
	v_pk_fma_f32 v[40:41], v[196:197], v[228:229], v[40:41] op_sel_hi:[1,0,1]
	v_pk_fma_f32 v[42:43], v[198:199], v[228:229], v[42:43] op_sel_hi:[1,0,1]
	v_pk_fma_f32 v[48:49], v[204:205], v[228:229], v[48:49] op_sel_hi:[1,0,1]
	v_pk_fma_f32 v[50:51], v[206:207], v[228:229], v[50:51] op_sel_hi:[1,0,1]
	v_pk_fma_f32 v[44:45], v[208:209], v[228:229], v[44:45] op_sel_hi:[1,0,1]
	v_pk_fma_f32 v[46:47], v[210:211], v[228:229], v[46:47] op_sel_hi:[1,0,1]
	v_pk_fma_f32 v[36:37], v[212:213], v[16:17], v[36:37] op_sel_hi:[1,0,1]
	v_pk_fma_f32 v[38:39], v[214:215], v[16:17], v[38:39] op_sel_hi:[1,0,1]
	v_pk_fma_f32 v[40:41], v[216:217], v[16:17], v[40:41] op_sel_hi:[1,0,1]
	v_pk_fma_f32 v[42:43], v[218:219], v[16:17], v[42:43] op_sel_hi:[1,0,1]
	v_pk_fma_f32 v[48:49], v[220:221], v[16:17], v[48:49] op_sel_hi:[1,0,1]
	v_pk_fma_f32 v[50:51], v[222:223], v[16:17], v[50:51] op_sel_hi:[1,0,1]
	v_pk_fma_f32 v[44:45], v[224:225], v[16:17], v[44:45] op_sel_hi:[1,0,1]
	v_pk_fma_f32 v[46:47], v[226:227], v[16:17], v[46:47] op_sel_hi:[1,0,1]
	v_pk_fma_f32 v[20:21], v[192:193], v[232:233], v[20:21] op_sel_hi:[1,0,1]
	v_pk_fma_f32 v[22:23], v[194:195], v[232:233], v[22:23] op_sel_hi:[1,0,1]
	v_pk_fma_f32 v[24:25], v[196:197], v[232:233], v[24:25] op_sel_hi:[1,0,1]
	v_pk_fma_f32 v[26:27], v[198:199], v[232:233], v[26:27] op_sel_hi:[1,0,1]
	v_pk_fma_f32 v[28:29], v[204:205], v[232:233], v[28:29] op_sel_hi:[1,0,1]
	v_pk_fma_f32 v[30:31], v[206:207], v[232:233], v[30:31] op_sel_hi:[1,0,1]
	v_pk_fma_f32 v[32:33], v[208:209], v[232:233], v[32:33] op_sel_hi:[1,0,1]
	v_pk_fma_f32 v[34:35], v[210:211], v[232:233], v[34:35] op_sel_hi:[1,0,1]
	ds_read_b128 v[192:195], v85 offset:1280
	ds_read_b128 v[196:199], v85 offset:1296
	ds_read_b128 v[204:207], v85 offset:1312
	ds_read_b128 v[208:211], v85 offset:1328
	ds_read_b128 v[212:215], v85 offset:1536
	ds_read_b128 v[216:219], v85 offset:1552
	ds_read_b128 v[220:223], v85 offset:1568
	ds_read_b128 v[224:227], v85 offset:1584
	ds_read_b32 v56, v111 offset:64
	ds_read_b128 v[168:171], v85 offset:1792
	ds_read_b128 v[172:175], v85 offset:1808
	ds_read_b128 v[184:187], v85 offset:1824
	ds_read_b128 v[188:191], v85 offset:1840
	ds_read_b128 v[128:131], v85 offset:2048
	ds_read_b128 v[132:135], v85 offset:2064
	ds_read_b128 v[136:139], v85 offset:2080
	ds_read_b128 v[140:143], v85 offset:2096
	v_pk_mul_f32 v[248:249], v[36:37], v[112:113]
	v_pk_mul_f32 v[252:253], v[20:21], v[112:113]
	v_pk_fma_f32 v[248:249], v[38:39], v[114:115], v[248:249]
	v_pk_fma_f32 v[252:253], v[22:23], v[114:115], v[252:253]
	v_pk_fma_f32 v[248:249], v[40:41], v[116:117], v[248:249]
	v_pk_fma_f32 v[252:253], v[24:25], v[116:117], v[252:253]
	v_pk_fma_f32 v[248:249], v[42:43], v[118:119], v[248:249]
	v_pk_fma_f32 v[252:253], v[26:27], v[118:119], v[252:253]
	v_pk_fma_f32 v[248:249], v[48:49], v[120:121], v[248:249]
	v_pk_fma_f32 v[252:253], v[28:29], v[120:121], v[252:253]
	v_pk_fma_f32 v[248:249], v[50:51], v[122:123], v[248:249]
	v_pk_fma_f32 v[252:253], v[30:31], v[122:123], v[252:253]
	v_pk_fma_f32 v[248:249], v[44:45], v[124:125], v[248:249]
	v_pk_fma_f32 v[252:253], v[32:33], v[124:125], v[252:253]
	v_pk_fma_f32 v[248:249], v[46:47], v[126:127], v[248:249]
	v_pk_fma_f32 v[252:253], v[34:35], v[126:127], v[252:253]
	v_add_f32_e32 v2, v248, v249
	v_add_f32_e32 v18, v252, v253
	v_pk_mul_f32 v[4:5], v[36:37], v[144:145]
	v_pk_mul_f32 v[8:9], v[20:21], v[144:145]
	v_mfma_f32_16x16x4_f32 v[228:231], v61, v2, 0
	v_pk_fma_f32 v[4:5], v[38:39], v[146:147], v[4:5]
	v_pk_fma_f32 v[8:9], v[22:23], v[146:147], v[8:9]
	v_mfma_f32_16x16x4_f32 v[232:235], v61, v18, 0
	v_pk_fma_f32 v[4:5], v[40:41], v[148:149], v[4:5]
	v_pk_fma_f32 v[8:9], v[24:25], v[148:149], v[8:9]
	v_pk_fma_f32 v[4:5], v[42:43], v[150:151], v[4:5]
	v_pk_fma_f32 v[8:9], v[26:27], v[150:151], v[8:9]
	v_pk_fma_f32 v[4:5], v[48:49], v[154:155], v[4:5]
	v_pk_fma_f32 v[8:9], v[28:29], v[154:155], v[8:9]
	v_pk_fma_f32 v[4:5], v[50:51], v[156:157], v[4:5]
	v_pk_fma_f32 v[8:9], v[30:31], v[156:157], v[8:9]
	v_pk_fma_f32 v[4:5], v[44:45], v[158:159], v[4:5]
	v_pk_fma_f32 v[8:9], v[32:33], v[158:159], v[8:9]
	v_pk_fma_f32 v[4:5], v[46:47], v[160:161], v[4:5]
	v_pk_fma_f32 v[8:9], v[34:35], v[160:161], v[8:9]
	v_add_f32_e32 v153, v4, v5
	v_add_f32_e32 v179, v8, v9
	s_nop 1
	v_mfma_f32_16x16x4_f32 v[236:239], v61, v153, 0
	v_mfma_f32_16x16x4_f32 v[244:247], v61, v179, 0
	s_waitcnt lgkmcnt(0)
; #define LAS __attribute__((address_space(3)))
; __device__ __forceinline__ float ksum(float p) { const f32x4 z = (f32x4){0.f, 0.f, 0.f, 0.f}; const f32x4 d = __builtin_amdgcn_mfma_f32_16x16x4f32(1.0f, p, z, 0, 0, 0); return d[0]; }
; #define RW_LD4(dst, P) do { _Pragma("unroll") for (int e = 0; e < 4; ++e) dst[e] = *(const LAS f32x4*)((P) + e * 16); } while (0)
; __device__ __forceinline__ float dot16(const f32x4 (&S)[4], const f32x4 (&a)[4]) {
;     f32x2 p0 = (f32x2){S[0][0], S[0][1]} * (f32x2){a[0][0], a[0][1]}, p1 = (f32x2){S[0][2], S[0][3]} * (f32x2){a[0][2], a[0][3]};
; #pragma unroll
;     for (int q = 1; q < 4; ++q) { p0 = __builtin_elementwise_fma((f32x2){S[q][0], S[q][1]}, (f32x2){a[q][0], a[q][1]}, p0); p1 = __builtin_elementwise_fma((f32x2){S[q][2], S[q][3]}, (f32x2){a[q][2], a[q][3]}, p1); }
;     const f32x2 t = p0 + p1; return t[0] + t[1];
; }
; template <bool useB>
; __device__ __forceinline__ void rw_block4(ScanState& st, const LAS unsigned char* pb, const LAS float* pv, float* outA, float* outB, int kg) {
;     ...
;     for (int ss = 0; ss < 4; ++ss) {
;         const bool more = ss < 3;
;         const LAS unsigned char* pn = pb + (ss + 1) * 1024; const LAS float* vn = pv + (ss + 1) * 16;
;         const float pa = dot16(st.A, oa), pq = useB ? dot16(st.B, oa) : 0.f;
;         const f32x4 da = __builtin_amdgcn_mfma_f32_16x16x4f32(1.0f, pa, z, 0, 0, 0);
;         f32x4 db = z; if (useB) db = __builtin_amdgcn_mfma_f32_16x16x4f32(1.0f, pq, z, 0, 0, 0);
;         if (more) RW_LD4(oa, pn);
;         if (ss > 0) { const float y = ksum(dot16(st.A, orr[(ss + 1) & 1])); ykA = (kg == ss - 1) ? y : ykA;
;             if (useB) { const float c = ksum(dot16(st.B, orr[(ss + 1) & 1])); ykB = (kg == ss - 1) ? c : ykB; } }
;         if (more) RW_LD4(orr[(ss + 1) & 1], pn + 768);
;         const float sa = da[0], sb = db[0];
;         const f32x4 sa4 = (f32x4){sa, sa, sa, sa}, sb4 = (f32x4){sb, sb, sb, sb}, v4 = (f32x4){ov, ov, ov, ov};
; #pragma unroll
;         for (int e = 0; e < 4; ++e) { st.A[e] = __builtin_elementwise_fma(ob[e], sa4, st.A[e]); st.A[e] = __builtin_elementwise_fma(ok[e], v4, st.A[e]); if (useB) st.B[e] = __builtin_elementwise_fma(ob[e], sb4, st.B[e]); }
;         if (more) { RW_LD4(ob, pn + 256); RW_LD4(ok, pn + 512); ov = *vn; }
	v_pk_fma_f32 v[36:37], v[192:193], v[228:229], v[36:37] op_sel_hi:[1,0,1]
	v_pk_fma_f32 v[38:39], v[194:195], v[228:229], v[38:39] op_sel_hi:[1,0,1]
	v_pk_fma_f32 v[40:41], v[196:197], v[228:229], v[40:41] op_sel_hi:[1,0,1]
	v_pk_fma_f32 v[42:43], v[198:199], v[228:229], v[42:43] op_sel_hi:[1,0,1]
	v_pk_fma_f32 v[48:49], v[204:205], v[228:229], v[48:49] op_sel_hi:[1,0,1]
	v_pk_fma_f32 v[50:51], v[206:207], v[228:229], v[50:51] op_sel_hi:[1,0,1]
	v_pk_fma_f32 v[44:45], v[208:209], v[228:229], v[44:45] op_sel_hi:[1,0,1]
	v_pk_fma_f32 v[46:47], v[210:211], v[228:229], v[46:47] op_sel_hi:[1,0,1]
	v_pk_fma_f32 v[36:37], v[212:213], v[56:57], v[36:37] op_sel_hi:[1,0,1]
	v_pk_fma_f32 v[38:39], v[214:215], v[56:57], v[38:39] op_sel_hi:[1,0,1]
	v_pk_fma_f32 v[40:41], v[216:217], v[56:57], v[40:41] op_sel_hi:[1,0,1]
	v_pk_fma_f32 v[42:43], v[218:219], v[56:57], v[42:43] op_sel_hi:[1,0,1]
	v_pk_fma_f32 v[48:49], v[220:221], v[56:57], v[48:49] op_sel_hi:[1,0,1]
	v_pk_fma_f32 v[50:51], v[222:223], v[56:57], v[50:51] op_sel_hi:[1,0,1]
	v_pk_fma_f32 v[44:45], v[224:225], v[56:57], v[44:45] op_sel_hi:[1,0,1]
	v_pk_fma_f32 v[46:47], v[226:227], v[56:57], v[46:47] op_sel_hi:[1,0,1]
	v_cndmask_b32_e64 v203, 0, v236, s[8:9]
	v_cndmask_b32_e64 v241, 0, v244, s[8:9]
	v_pk_fma_f32 v[20:21], v[192:193], v[232:233], v[20:21] op_sel_hi:[1,0,1]
	v_pk_fma_f32 v[22:23], v[194:195], v[232:233], v[22:23] op_sel_hi:[1,0,1]
	v_pk_fma_f32 v[24:25], v[196:197], v[232:233], v[24:25] op_sel_hi:[1,0,1]
	v_pk_fma_f32 v[26:27], v[198:199], v[232:233], v[26:27] op_sel_hi:[1,0,1]
	v_pk_fma_f32 v[28:29], v[204:205], v[232:233], v[28:29] op_sel_hi:[1,0,1]
	v_pk_fma_f32 v[30:31], v[206:207], v[232:233], v[30:31] op_sel_hi:[1,0,1]
	v_pk_fma_f32 v[32:33], v[208:209], v[232:233], v[32:33] op_sel_hi:[1,0,1]
	v_pk_fma_f32 v[34:35], v[210:211], v[232:233], v[34:35] op_sel_hi:[1,0,1]
	ds_read_b128 v[192:195], v85 offset:2304
	ds_read_b128 v[196:199], v85 offset:2320
	ds_read_b128 v[204:207], v85 offset:2336
	ds_read_b128 v[208:211], v85 offset:2352
	ds_read_b128 v[212:215], v85 offset:2560
	ds_read_b128 v[216:219], v85 offset:2576
	ds_read_b128 v[220:223], v85 offset:2592
	ds_read_b128 v[224:227], v85 offset:2608
	ds_read_b32 v16, v111 offset:128
	ds_read_b128 v[144:147], v85 offset:2816
	ds_read_b128 v[148:151], v85 offset:2832
	ds_read_b128 v[154:157], v85 offset:2848
	ds_read_b128 v[158:161], v85 offset:2864
	ds_read_b128 v[112:115], v85 offset:3072
	ds_read_b128 v[116:119], v85 offset:3088
	ds_read_b128 v[120:123], v85 offset:3104
	ds_read_b128 v[124:127], v85 offset:3120
	v_pk_mul_f32 v[248:249], v[36:37], v[128:129]
	v_pk_mul_f32 v[252:253], v[20:21], v[128:129]
	v_pk_fma_f32 v[248:249], v[38:39], v[130:131], v[248:249]
	v_pk_fma_f32 v[252:253], v[22:23], v[130:131], v[252:253]
	v_pk_fma_f32 v[248:249], v[40:41], v[132:133], v[248:249]
	v_pk_fma_f32 v[252:253], v[24:25], v[132:133], v[252:253]
	v_pk_fma_f32 v[248:249], v[42:43], v[134:135], v[248:249]
	v_pk_fma_f32 v[252:253], v[26:27], v[134:135], v[252:253]
	v_pk_fma_f32 v[248:249], v[48:49], v[136:137], v[248:249]
	v_pk_fma_f32 v[252:253], v[28:29], v[136:137], v[252:253]
	v_pk_fma_f32 v[248:249], v[50:51], v[138:139], v[248:249]
	v_pk_fma_f32 v[252:253], v[30:31], v[138:139], v[252:253]
	v_pk_fma_f32 v[248:249], v[44:45], v[140:141], v[248:249]
	v_pk_fma_f32 v[252:253], v[32:33], v[140:141], v[252:253]
	v_pk_fma_f32 v[248:249], v[46:47], v[142:143], v[248:249]
	v_pk_fma_f32 v[252:253], v[34:35], v[142:143], v[252:253]
	v_add_f32_e32 v2, v248, v249
	v_add_f32_e32 v18, v252, v253
	v_pk_mul_f32 v[4:5], v[36:37], v[168:169]
	v_pk_mul_f32 v[8:9], v[20:21], v[168:169]
	v_mfma_f32_16x16x4_f32 v[228:231], v61, v2, 0
	v_pk_fma_f32 v[4:5], v[38:39], v[170:171], v[4:5]
	v_pk_fma_f32 v[8:9], v[22:23], v[170:171], v[8:9]
	v_mfma_f32_16x16x4_f32 v[232:235], v61, v18, 0
	v_pk_fma_f32 v[4:5], v[40:41], v[172:173], v[4:5]
	v_pk_fma_f32 v[8:9], v[24:25], v[172:173], v[8:9]
	v_pk_fma_f32 v[4:5], v[42:43], v[174:175], v[4:5]
	v_pk_fma_f32 v[8:9], v[26:27], v[174:175], v[8:9]
	v_pk_fma_f32 v[4:5], v[48:49], v[184:185], v[4:5]
	v_pk_fma_f32 v[8:9], v[28:29], v[184:185], v[8:9]
	v_pk_fma_f32 v[4:5], v[50:51], v[186:187], v[4:5]
	v_pk_fma_f32 v[8:9], v[30:31], v[186:187], v[8:9]
	v_pk_fma_f32 v[4:5], v[44:45], v[188:189], v[4:5]
	v_pk_fma_f32 v[8:9], v[32:33], v[188:189], v[8:9]
	v_pk_fma_f32 v[4:5], v[46:47], v[190:191], v[4:5]
	v_pk_fma_f32 v[8:9], v[34:35], v[190:191], v[8:9]
	v_add_f32_e32 v153, v4, v5
	v_add_f32_e32 v179, v8, v9
	s_nop 1
	v_mfma_f32_16x16x4_f32 v[236:239], v61, v153, 0
	v_mfma_f32_16x16x4_f32 v[244:247], v61, v179, 0
	s_waitcnt lgkmcnt(0)
; #define LAS __attribute__((address_space(3)))
; __device__ __forceinline__ float ksum(float p) { const f32x4 z = (f32x4){0.f, 0.f, 0.f, 0.f}; const f32x4 d = __builtin_amdgcn_mfma_f32_16x16x4f32(1.0f, p, z, 0, 0, 0); return d[0]; }
; #define RW_LD4(dst, P) do { _Pragma("unroll") for (int e = 0; e < 4; ++e) dst[e] = *(const LAS f32x4*)((P) + e * 16); } while (0)
; __device__ __forceinline__ float dot16(const f32x4 (&S)[4], const f32x4 (&a)[4]) {
;     f32x2 p0 = (f32x2){S[0][0], S[0][1]} * (f32x2){a[0][0], a[0][1]}, p1 = (f32x2){S[0][2], S[0][3]} * (f32x2){a[0][2], a[0][3]};
; #pragma unroll
;     for (int q = 1; q < 4; ++q) { p0 = __builtin_elementwise_fma((f32x2){S[q][0], S[q][1]}, (f32x2){a[q][0], a[q][1]}, p0); p1 = __builtin_elementwise_fma((f32x2){S[q][2], S[q][3]}, (f32x2){a[q][2], a[q][3]}, p1); }
;     const f32x2 t = p0 + p1; return t[0] + t[1];
; }
; template <bool useB>
; __device__ __forceinline__ void rw_block4(ScanState& st, const LAS unsigned char* pb, const LAS float* pv, float* outA, float* outB, int kg) {
;     ...
;     for (int ss = 0; ss < 4; ++ss) {
;         const bool more = ss < 3;
;         const LAS unsigned char* pn = pb + (ss + 1) * 1024; const LAS float* vn = pv + (ss + 1) * 16;
;         const float pa = dot16(st.A, oa), pq = useB ? dot16(st.B, oa) : 0.f;
;         const f32x4 da = __builtin_amdgcn_mfma_f32_16x16x4f32(1.0f, pa, z, 0, 0, 0);
;         f32x4 db = z; if (useB) db = __builtin_amdgcn_mfma_f32_16x16x4f32(1.0f, pq, z, 0, 0, 0);
;         if (more) RW_LD4(oa, pn);
;         if (ss > 0) { const float y = ksum(dot16(st.A, orr[(ss + 1) & 1])); ykA = (kg == ss - 1) ? y : ykA;
;             if (useB) { const float c = ksum(dot16(st.B, orr[(ss + 1) & 1])); ykB = (kg == ss - 1) ? c : ykB; } }
;         if (more) RW_LD4(orr[(ss + 1) & 1], pn + 768);
;         const float sa = da[0], sb = db[0];
;         const f32x4 sa4 = (f32x4){sa, sa, sa, sa}, sb4 = (f32x4){sb, sb, sb, sb}, v4 = (f32x4){ov, ov, ov, ov};
; #pragma unroll
;         for (int e = 0; e < 4; ++e) { st.A[e] = __builtin_elementwise_fma(ob[e], sa4, st.A[e]); st.A[e] = __builtin_elementwise_fma(ok[e], v4, st.A[e]); if (useB) st.B[e] = __builtin_elementwise_fma(ob[e], sb4, st.B[e]); }
;         if (more) { RW_LD4(ob, pn + 256); RW_LD4(ok, pn + 512); ov = *vn; }
	v_pk_fma_f32 v[36:37], v[192:193], v[228:229], v[36:37] op_sel_hi:[1,0,1]
	v_pk_fma_f32 v[38:39], v[194:195], v[228:229], v[38:39] op_sel_hi:[1,0,1]
	v_pk_fma_f32 v[40:41], v[196:197], v[228:229], v[40:41] op_sel_hi:[1,0,1]
	v_pk_fma_f32 v[42:43], v[198:199], v[228:229], v[42:43] op_sel_hi:[1,0,1]
	v_pk_fma_f32 v[48:49], v[204:205], v[228:229], v[48:49] op_sel_hi:[1,0,1]
	v_pk_fma_f32 v[50:51], v[206:207], v[228:229], v[50:51] op_sel_hi:[1,0,1]
	v_pk_fma_f32 v[44:45], v[208:209], v[228:229], v[44:45] op_sel_hi:[1,0,1]
	v_pk_fma_f32 v[46:47], v[210:211], v[228:229], v[46:47] op_sel_hi:[1,0,1]
	v_pk_fma_f32 v[36:37], v[212:213], v[16:17], v[36:37] op_sel_hi:[1,0,1]
	v_pk_fma_f32 v[38:39], v[214:215], v[16:17], v[38:39] op_sel_hi:[1,0,1]
	v_pk_fma_f32 v[40:41], v[216:217], v[16:17], v[40:41] op_sel_hi:[1,0,1]
	v_pk_fma_f32 v[42:43], v[218:219], v[16:17], v[42:43] op_sel_hi:[1,0,1]
	v_pk_fma_f32 v[48:49], v[220:221], v[16:17], v[48:49] op_sel_hi:[1,0,1]
	v_pk_fma_f32 v[50:51], v[222:223], v[16:17], v[50:51] op_sel_hi:[1,0,1]
	v_pk_fma_f32 v[44:45], v[224:225], v[16:17], v[44:45] op_sel_hi:[1,0,1]
	v_pk_fma_f32 v[46:47], v[226:227], v[16:17], v[46:47] op_sel_hi:[1,0,1]
	v_cndmask_b32_e64 v203, v203, v236, s[12:13]
	v_cndmask_b32_e64 v241, v241, v244, s[12:13]
	v_pk_fma_f32 v[20:21], v[192:193], v[232:233], v[20:21] op_sel_hi:[1,0,1]
	v_pk_fma_f32 v[22:23], v[194:195], v[232:233], v[22:23] op_sel_hi:[1,0,1]
	v_pk_fma_f32 v[24:25], v[196:197], v[232:233], v[24:25] op_sel_hi:[1,0,1]
	v_pk_fma_f32 v[26:27], v[198:199], v[232:233], v[26:27] op_sel_hi:[1,0,1]
	v_pk_fma_f32 v[28:29], v[204:205], v[232:233], v[28:29] op_sel_hi:[1,0,1]
	v_pk_fma_f32 v[30:31], v[206:207], v[232:233], v[30:31] op_sel_hi:[1,0,1]
	v_pk_fma_f32 v[32:33], v[208:209], v[232:233], v[32:33] op_sel_hi:[1,0,1]
	v_pk_fma_f32 v[34:35], v[210:211], v[232:233], v[34:35] op_sel_hi:[1,0,1]
	ds_read_b128 v[192:195], v85 offset:3328
	ds_read_b128 v[196:199], v85 offset:3344
	ds_read_b128 v[204:207], v85 offset:3360
	ds_read_b128 v[208:211], v85 offset:3376
	ds_read_b128 v[212:215], v85 offset:3584
	ds_read_b128 v[216:219], v85 offset:3600
	ds_read_b128 v[220:223], v85 offset:3616
	ds_read_b128 v[224:227], v85 offset:3632
	ds_read_b32 v56, v111 offset:192
	ds_read_b128 v[168:171], v85 offset:3840
	ds_read_b128 v[172:175], v85 offset:3856
	ds_read_b128 v[184:187], v85 offset:3872
	ds_read_b128 v[188:191], v85 offset:3888
	v_pk_mul_f32 v[248:249], v[36:37], v[112:113]
	v_pk_mul_f32 v[252:253], v[20:21], v[112:113]
	v_pk_fma_f32 v[248:249], v[38:39], v[114:115], v[248:249]
	v_pk_fma_f32 v[252:253], v[22:23], v[114:115], v[252:253]
	v_pk_fma_f32 v[248:249], v[40:41], v[116:117], v[248:249]
	v_pk_fma_f32 v[252:253], v[24:25], v[116:117], v[252:253]
	v_pk_fma_f32 v[248:249], v[42:43], v[118:119], v[248:249]
	v_pk_fma_f32 v[252:253], v[26:27], v[118:119], v[252:253]
	v_pk_fma_f32 v[248:249], v[48:49], v[120:121], v[248:249]
	v_pk_fma_f32 v[252:253], v[28:29], v[120:121], v[252:253]
	v_pk_fma_f32 v[248:249], v[50:51], v[122:123], v[248:249]
	v_pk_fma_f32 v[252:253], v[30:31], v[122:123], v[252:253]
	v_pk_fma_f32 v[248:249], v[44:45], v[124:125], v[248:249]
	v_pk_fma_f32 v[252:253], v[32:33], v[124:125], v[252:253]
	v_pk_fma_f32 v[248:249], v[46:47], v[126:127], v[248:249]
	v_pk_fma_f32 v[252:253], v[34:35], v[126:127], v[252:253]
	v_add_f32_e32 v2, v248, v249
	v_add_f32_e32 v18, v252, v253
	v_pk_mul_f32 v[4:5], v[36:37], v[144:145]
	v_pk_mul_f32 v[8:9], v[20:21], v[144:145]
	v_mfma_f32_16x16x4_f32 v[228:231], v61, v2, 0
	v_pk_fma_f32 v[4:5], v[38:39], v[146:147], v[4:5]
	v_pk_fma_f32 v[8:9], v[22:23], v[146:147], v[8:9]
	v_mfma_f32_16x16x4_f32 v[232:235], v61, v18, 0
	v_pk_fma_f32 v[4:5], v[40:41], v[148:149], v[4:5]
	v_pk_fma_f32 v[8:9], v[24:25], v[148:149], v[8:9]
	v_pk_fma_f32 v[4:5], v[42:43], v[150:151], v[4:5]
	v_pk_fma_f32 v[8:9], v[26:27], v[150:151], v[8:9]
	v_pk_fma_f32 v[4:5], v[48:49], v[154:155], v[4:5]
	v_pk_fma_f32 v[8:9], v[28:29], v[154:155], v[8:9]
	v_pk_fma_f32 v[4:5], v[50:51], v[156:157], v[4:5]
	v_pk_fma_f32 v[8:9], v[30:31], v[156:157], v[8:9]
	v_pk_fma_f32 v[4:5], v[44:45], v[158:159], v[4:5]
	v_pk_fma_f32 v[8:9], v[32:33], v[158:159], v[8:9]
	v_pk_fma_f32 v[4:5], v[46:47], v[160:161], v[4:5]
	v_pk_fma_f32 v[8:9], v[34:35], v[160:161], v[8:9]
	v_add_f32_e32 v153, v4, v5
	v_add_f32_e32 v179, v8, v9
	s_nop 1
	v_mfma_f32_16x16x4_f32 v[236:239], v61, v153, 0
	v_mfma_f32_16x16x4_f32 v[244:247], v61, v179, 0
	s_waitcnt lgkmcnt(0)
; #define LAS __attribute__((address_space(3)))
; __device__ __forceinline__ float ksum(float p) { const f32x4 z = (f32x4){0.f, 0.f, 0.f, 0.f}; const f32x4 d = __builtin_amdgcn_mfma_f32_16x16x4f32(1.0f, p, z, 0, 0, 0); return d[0]; }
; template <bool useB>
; __device__ __forceinline__ void rw_block4(ScanState& st, const LAS unsigned char* pb, const LAS float* pv, float* outA, float* outB, int kg) {
;     ...
;     for (int ss = 0; ss < 4; ++ss) {
;         const bool more = ss < 3;
;         const LAS unsigned char* pn = pb + (ss + 1) * 1024; const LAS float* vn = pv + (ss + 1) * 16;
;         const float pa = dot16(st.A, oa), pq = useB ? dot16(st.B, oa) : 0.f;
;         const f32x4 da = __builtin_amdgcn_mfma_f32_16x16x4f32(1.0f, pa, z, 0, 0, 0);
;         f32x4 db = z; if (useB) db = __builtin_amdgcn_mfma_f32_16x16x4f32(1.0f, pq, z, 0, 0, 0);
;         if (more) RW_LD4(oa, pn);
;         if (ss > 0) { const float y = ksum(dot16(st.A, orr[(ss + 1) & 1])); ykA = (kg == ss - 1) ? y : ykA;
;             if (useB) { const float c = ksum(dot16(st.B, orr[(ss + 1) & 1])); ykB = (kg == ss - 1) ? c : ykB; } }
;         if (more) RW_LD4(orr[(ss + 1) & 1], pn + 768);
;         const float sa = da[0], sb = db[0];
;         const f32x4 sa4 = (f32x4){sa, sa, sa, sa}, sb4 = (f32x4){sb, sb, sb, sb}, v4 = (f32x4){ov, ov, ov, ov};
; #pragma unroll
;         for (int e = 0; e < 4; ++e) { st.A[e] = __builtin_elementwise_fma(ob[e], sa4, st.A[e]); st.A[e] = __builtin_elementwise_fma(ok[e], v4, st.A[e]); if (useB) st.B[e] = __builtin_elementwise_fma(ob[e], sb4, st.B[e]); }
;         if (more) { RW_LD4(ob, pn + 256); RW_LD4(ok, pn + 512); ov = *vn; }
;     }
;     { const float y = ksum(dot16(st.A, orr[1])); ykA = (kg == 3) ? y : ykA; outA[(size_t)kg * DH] = ykA;
;       if (useB) { const float c = ksum(dot16(st.B, orr[1])); ykB = (kg == 3) ? c : ykB; outB[(size_t)kg * DH] = ykB; } }
; template <bool useB>
; __device__ __forceinline__ void rw_job(Frame& F, ScanState& st, int rec0, const float* vrow0, const float* wcp0, int nsteps, float* outA0, float* outB0, int w, int lane) {
;     ...
;         if ((b & 15) == 15 || b == nb - 1) {
; #pragma unroll
;             for (int e = 0; e < 4; ++e) { const f32x4 wc = *(const LAS f32x4*)(F.lds + 139264 + w * 512 + ((b >> 4) & 1) * 256 + kg * 64 + e * 16); st.A[e] = st.A[e] * wc; if (useB) st.B[e] = st.B[e] * wc; } }
	v_pk_fma_f32 v[36:37], v[192:193], v[228:229], v[36:37] op_sel_hi:[1,0,1]
	v_pk_fma_f32 v[38:39], v[194:195], v[228:229], v[38:39] op_sel_hi:[1,0,1]
	v_pk_fma_f32 v[40:41], v[196:197], v[228:229], v[40:41] op_sel_hi:[1,0,1]
	v_pk_fma_f32 v[42:43], v[198:199], v[228:229], v[42:43] op_sel_hi:[1,0,1]
	v_pk_fma_f32 v[48:49], v[204:205], v[228:229], v[48:49] op_sel_hi:[1,0,1]
	v_pk_fma_f32 v[50:51], v[206:207], v[228:229], v[50:51] op_sel_hi:[1,0,1]
	v_pk_fma_f32 v[44:45], v[208:209], v[228:229], v[44:45] op_sel_hi:[1,0,1]
	v_pk_fma_f32 v[46:47], v[210:211], v[228:229], v[46:47] op_sel_hi:[1,0,1]
	v_pk_fma_f32 v[36:37], v[212:213], v[56:57], v[36:37] op_sel_hi:[1,0,1]
	v_pk_fma_f32 v[38:39], v[214:215], v[56:57], v[38:39] op_sel_hi:[1,0,1]
	v_pk_fma_f32 v[40:41], v[216:217], v[56:57], v[40:41] op_sel_hi:[1,0,1]
	v_pk_fma_f32 v[42:43], v[218:219], v[56:57], v[42:43] op_sel_hi:[1,0,1]
	v_pk_fma_f32 v[48:49], v[220:221], v[56:57], v[48:49] op_sel_hi:[1,0,1]
	v_pk_fma_f32 v[50:51], v[222:223], v[56:57], v[50:51] op_sel_hi:[1,0,1]
	v_pk_fma_f32 v[44:45], v[224:225], v[56:57], v[44:45] op_sel_hi:[1,0,1]
	v_pk_fma_f32 v[46:47], v[226:227], v[56:57], v[46:47] op_sel_hi:[1,0,1]
	v_cndmask_b32_e64 v203, v203, v236, s[10:11]
	v_cndmask_b32_e64 v241, v241, v244, s[10:11]
	v_pk_fma_f32 v[20:21], v[192:193], v[232:233], v[20:21] op_sel_hi:[1,0,1]
	v_pk_fma_f32 v[22:23], v[194:195], v[232:233], v[22:23] op_sel_hi:[1,0,1]
	v_pk_fma_f32 v[24:25], v[196:197], v[232:233], v[24:25] op_sel_hi:[1,0,1]
	v_pk_fma_f32 v[26:27], v[198:199], v[232:233], v[26:27] op_sel_hi:[1,0,1]
	v_pk_fma_f32 v[28:29], v[204:205], v[232:233], v[28:29] op_sel_hi:[1,0,1]
	v_pk_fma_f32 v[30:31], v[206:207], v[232:233], v[30:31] op_sel_hi:[1,0,1]
	v_pk_fma_f32 v[32:33], v[208:209], v[232:233], v[32:33] op_sel_hi:[1,0,1]
	v_pk_fma_f32 v[34:35], v[210:211], v[232:233], v[34:35] op_sel_hi:[1,0,1]
	v_pk_mul_f32 v[4:5], v[36:37], v[168:169]
	v_pk_fma_f32 v[4:5], v[38:39], v[170:171], v[4:5]
	v_pk_fma_f32 v[4:5], v[40:41], v[172:173], v[4:5]
	v_pk_fma_f32 v[4:5], v[42:43], v[174:175], v[4:5]
	v_pk_fma_f32 v[4:5], v[48:49], v[184:185], v[4:5]
	v_pk_fma_f32 v[4:5], v[50:51], v[186:187], v[4:5]
	v_pk_fma_f32 v[4:5], v[44:45], v[188:189], v[4:5]
	v_pk_fma_f32 v[4:5], v[46:47], v[190:191], v[4:5]
	v_add_f32_e32 v153, v4, v5
	v_pk_mul_f32 v[8:9], v[20:21], v[168:169]
	v_pk_fma_f32 v[8:9], v[22:23], v[170:171], v[8:9]
	v_mfma_f32_16x16x4_f32 v[236:239], v61, v153, 0
	v_pk_fma_f32 v[8:9], v[24:25], v[172:173], v[8:9]
	v_pk_fma_f32 v[8:9], v[26:27], v[174:175], v[8:9]
	v_pk_fma_f32 v[8:9], v[28:29], v[184:185], v[8:9]
	v_pk_fma_f32 v[8:9], v[30:31], v[186:187], v[8:9]
	v_pk_fma_f32 v[8:9], v[32:33], v[188:189], v[8:9]
	v_pk_fma_f32 v[8:9], v[34:35], v[190:191], v[8:9]
	v_add_f32_e32 v179, v8, v9
	v_lshl_add_u64 v[12:13], v[90:91], 0, s[24:25]
	v_lshl_add_u64 v[14:15], v[92:93], 0, s[24:25]
	v_mfma_f32_16x16x4_f32 v[244:247], v61, v179, 0
	s_nop 9
	v_cndmask_b32_e64 v203, v203, v236, s[14:15]
	v_cndmask_b32_e64 v241, v241, v244, s[14:15]
	global_store_dword v[12:13], v203, off
	global_store_dword v[14:15], v241, off
	s_and_b32 s0, s51, 15
	s_cmp_lg_u32 s0, 15
	s_cbranch_scc1 .LBB0_1026
	s_and_b32 s0, s50, 0x100
	v_add_u32_e32 v52, s0, v108
	v_add_u32_e32 v56, s0, v109
	ds_read_b128 v[52:55], v52
	v_add_u32_e32 v57, 0x22010, v56
	ds_read_b128 v[112:115], v57
	s_waitcnt lgkmcnt(0)
	v_pk_mul_f32 v[36:37], v[36:37], v[52:53]
	v_pk_mul_f32 v[20:21], v[20:21], v[52:53]
	v_add_u32_e32 v52, 0x22020, v56
	v_add_u32_e32 v56, 0x22030, v56
	v_pk_mul_f32 v[38:39], v[38:39], v[54:55]
	v_pk_mul_f32 v[22:23], v[22:23], v[54:55]
	v_pk_mul_f32 v[42:43], v[42:43], v[114:115]
	v_pk_mul_f32 v[40:41], v[40:41], v[112:113]
	ds_read_b128 v[52:55], v52
	v_pk_mul_f32 v[26:27], v[26:27], v[114:115]
	v_pk_mul_f32 v[24:25], v[24:25], v[112:113]
	ds_read_b128 v[112:115], v56
	s_waitcnt lgkmcnt(0)
	v_pk_mul_f32 v[50:51], v[50:51], v[54:55]
	v_pk_mul_f32 v[48:49], v[48:49], v[52:53]
	v_pk_mul_f32 v[30:31], v[30:31], v[54:55]
	v_pk_mul_f32 v[28:29], v[28:29], v[52:53]
	v_pk_mul_f32 v[46:47], v[46:47], v[114:115]
	v_pk_mul_f32 v[44:45], v[44:45], v[112:113]
	v_pk_mul_f32 v[34:35], v[34:35], v[114:115]
	v_pk_mul_f32 v[32:33], v[32:33], v[112:113]
	s_branch .LBB0_1026
